# v12 plus write-through (sc0 sc1) stores in P0, P1 epilogue and pass A so the grid barriers' L2 writeback has nothing left to flush
# speedup vs baseline: 1.0053x; 1.0053x over previous
.LBB0_20:
	s_waitcnt vmcnt(30)
	ds_write2_b32 v20, v21, v22 offset1:66
	s_waitcnt vmcnt(28)
	ds_write2_b32 v20, v23, v25 offset0:132 offset1:198
	v_add_u32_e32 v21, 0x400, v20
	s_waitcnt vmcnt(26)
	ds_write2_b32 v21, v24, v26 offset0:8 offset1:74
	s_waitcnt vmcnt(24)
	ds_write2_b32 v21, v27, v28 offset0:140 offset1:206
	v_add_u32_e32 v21, 0x800, v20
	s_waitcnt vmcnt(22)
	ds_write2_b32 v21, v29, v30 offset0:16 offset1:82
	s_waitcnt vmcnt(20)
	ds_write2_b32 v21, v31, v33 offset0:148 offset1:214
	v_add_u32_e32 v21, 0xc00, v20
	s_waitcnt vmcnt(18)
	ds_write2_b32 v21, v32, v34 offset0:24 offset1:90
	s_waitcnt vmcnt(16)
	ds_write2_b32 v21, v35, v36 offset0:156 offset1:222
	v_add_u32_e32 v21, 0x1000, v20
	s_waitcnt vmcnt(14)
	ds_write2_b32 v21, v37, v38 offset0:32 offset1:98
	s_waitcnt vmcnt(12)
	ds_write2_b32 v21, v39, v41 offset0:164 offset1:230
	v_add_u32_e32 v21, 0x1400, v20
	s_waitcnt vmcnt(10)
	ds_write2_b32 v21, v40, v42 offset0:40 offset1:106
	s_waitcnt vmcnt(8)
	ds_write2_b32 v21, v43, v44 offset0:172 offset1:238
	v_add_u32_e32 v21, 0x1800, v20
	s_waitcnt vmcnt(6)
	ds_write2_b32 v21, v45, v46 offset0:48 offset1:114
	s_waitcnt vmcnt(4)
	ds_write2_b32 v21, v47, v49 offset0:180 offset1:246
	v_add_u32_e32 v21, 0x1c00, v20
	s_waitcnt vmcnt(2)
	ds_write2_b32 v21, v48, v50 offset0:56 offset1:122
	s_waitcnt vmcnt(0)
	ds_write2_b32 v21, v51, v52 offset0:188 offset1:254
	s_waitcnt lgkmcnt(0)
	ds_read2_b32 v[26:27], v19 offset1:8
	ds_read2_b32 v[28:29], v19 offset0:33 offset1:41
	ds_read2_b32 v[32:33], v19 offset0:66 offset1:74
	ds_read2_b32 v[34:35], v19 offset0:99 offset1:107
	ds_read2_b32 v[36:37], v19 offset0:132 offset1:140
	ds_read2_b32 v[38:39], v19 offset0:165 offset1:173
	ds_read2_b32 v[40:41], v19 offset0:198 offset1:206
	ds_read2_b32 v[42:43], v19 offset0:231 offset1:239
	s_waitcnt lgkmcnt(7)
	v_mov_b32_e32 v22, v26
	s_waitcnt lgkmcnt(6)
	v_mov_b32_e32 v23, v28
	s_waitcnt lgkmcnt(5)
	v_mov_b32_e32 v24, v32
	s_waitcnt lgkmcnt(4)
	v_mov_b32_e32 v25, v34
	v_pk_mul_f32 v[22:23], v[4:5], v[22:23]
	v_pk_mul_f32 v[24:25], v[6:7], v[24:25]
	v_cvt_pk_bf16_f32 v22, v22, v23
	v_cvt_pk_bf16_f32 v23, v24, v25
	s_waitcnt lgkmcnt(3)
	v_mov_b32_e32 v24, v36
	s_waitcnt lgkmcnt(2)
	v_mov_b32_e32 v25, v38
	s_waitcnt lgkmcnt(1)
	v_mov_b32_e32 v44, v40
	s_waitcnt lgkmcnt(0)
	v_mov_b32_e32 v45, v42
	v_pk_mul_f32 v[24:25], v[0:1], v[24:25]
	v_pk_mul_f32 v[44:45], v[2:3], v[44:45]
	v_cvt_pk_bf16_f32 v24, v24, v25
	v_cvt_pk_bf16_f32 v25, v44, v45
	v_add_u32_e32 v44, s2, v18
	v_ashrrev_i32_e32 v45, 31, v44
	v_lshl_add_u64 v[30:31], s[4:5], 1, v[12:13]
	v_lshlrev_b64 v[46:47], 11, v[44:45]
	v_lshl_add_u64 v[46:47], v[30:31], 0, v[46:47]
	v_mov_b32_e32 v28, v27
	v_mov_b32_e32 v34, v33
	global_store_dwordx4 v[46:47], v[22:25], off sc0 sc1
	v_mov_b32_e32 v38, v37
	v_mov_b32_e32 v42, v41
	v_pk_mul_f32 v[22:23], v[4:5], v[28:29]
	v_pk_mul_f32 v[24:25], v[6:7], v[34:35]
	v_cvt_pk_bf16_f32 v22, v22, v23
	v_cvt_pk_bf16_f32 v23, v24, v25
	v_pk_mul_f32 v[24:25], v[0:1], v[38:39]
	v_pk_mul_f32 v[26:27], v[2:3], v[42:43]
	v_cvt_pk_bf16_f32 v24, v24, v25
	v_cvt_pk_bf16_f32 v25, v26, v27
	v_add_u32_e32 v26, 8, v44
	v_ashrrev_i32_e32 v27, 31, v26
	v_lshlrev_b64 v[26:27], 11, v[26:27]
	v_lshl_add_u64 v[26:27], v[30:31], 0, v[26:27]
	ds_read2_b32 v[28:29], v19 offset0:16 offset1:24
	ds_read2_b32 v[32:33], v19 offset0:49 offset1:57
	global_store_dwordx4 v[26:27], v[22:25], off sc0 sc1
	ds_read2_b32 v[26:27], v19 offset0:82 offset1:90
	ds_read2_b32 v[34:35], v19 offset0:115 offset1:123
	ds_read2_b32 v[36:37], v19 offset0:148 offset1:156
	ds_read2_b32 v[38:39], v19 offset0:181 offset1:189
	ds_read2_b32 v[40:41], v19 offset0:214 offset1:222
	ds_read2_b32 v[42:43], v19 offset0:247 offset1:255
	s_waitcnt lgkmcnt(7)
	v_mov_b32_e32 v22, v28
	s_waitcnt lgkmcnt(6)
	v_mov_b32_e32 v23, v32
	s_waitcnt lgkmcnt(5)
	v_mov_b32_e32 v24, v26
	s_waitcnt lgkmcnt(4)
	v_mov_b32_e32 v25, v34
	v_pk_mul_f32 v[22:23], v[4:5], v[22:23]
	v_pk_mul_f32 v[24:25], v[6:7], v[24:25]
	v_cvt_pk_bf16_f32 v22, v22, v23
	v_cvt_pk_bf16_f32 v23, v24, v25
	s_waitcnt lgkmcnt(3)
	v_mov_b32_e32 v24, v36
	s_waitcnt lgkmcnt(2)
	v_mov_b32_e32 v25, v38
	v_mov_b32_e32 v32, v29
	v_mov_b32_e32 v34, v27
	v_mov_b32_e32 v38, v37
	v_pk_mul_f32 v[24:25], v[0:1], v[24:25]
	s_waitcnt lgkmcnt(1)
	v_mov_b32_e32 v46, v40
	s_waitcnt lgkmcnt(0)
	v_mov_b32_e32 v47, v42
	v_pk_mul_f32 v[4:5], v[4:5], v[32:33]
	v_pk_mul_f32 v[6:7], v[6:7], v[34:35]
	v_pk_mul_f32 v[0:1], v[0:1], v[38:39]
	v_mov_b32_e32 v42, v41
	v_pk_mul_f32 v[46:47], v[2:3], v[46:47]
	v_cvt_pk_bf16_f32 v4, v4, v5
	v_cvt_pk_bf16_f32 v5, v6, v7
	v_cvt_pk_bf16_f32 v6, v0, v1
	v_pk_mul_f32 v[0:1], v[2:3], v[42:43]
	v_cvt_pk_bf16_f32 v24, v24, v25
	v_cvt_pk_bf16_f32 v25, v46, v47
	v_add_u32_e32 v46, 16, v44
	v_cvt_pk_bf16_f32 v7, v0, v1
	v_add_u32_e32 v0, 24, v44
	v_ashrrev_i32_e32 v47, 31, v46
	v_ashrrev_i32_e32 v1, 31, v0
	v_lshlrev_b64 v[46:47], 11, v[46:47]
	v_lshlrev_b64 v[0:1], 11, v[0:1]
	v_lshl_add_u64 v[46:47], v[30:31], 0, v[46:47]
	v_lshl_add_u64 v[0:1], v[30:31], 0, v[0:1]
	global_store_dwordx4 v[46:47], v[22:25], off sc0 sc1
	global_store_dwordx4 v[0:1], v[4:7], off sc0 sc1
	s_waitcnt lgkmcnt(0)
	v_readlane_b32 s2, v233, 7
	s_add_i32 s39, s39, s2
	s_add_i32 s6, s6, s7
	s_cmpk_gt_i32 s39, 0xeff
	s_cbranch_scc1 .LBB0_23

.LBB0_26:
	s_or_b64 exec, exec, s[0:1]
	s_waitcnt vmcnt(0)
	v_cvt_pk_bf16_f32 v10, v3, v11
	v_ashrrev_i32_e32 v3, 31, v2
	v_lshlrev_b64 v[2:3], 9, v[2:3]
	v_add_u32_e32 v6, s52, v6
	v_cvt_pk_bf16_f32 v11, v12, v13
	v_cvt_pk_bf16_f32 v13, v16, v0
	v_lshl_add_u64 v[2:3], s[24:25], 0, v[2:3]
	v_lshlrev_b32_e32 v0, 1, v9
	v_cmp_lt_i32_e32 vcc, s28, v6
	v_cvt_pk_bf16_f32 v12, v14, v15
	v_lshl_add_u64 v[2:3], v[2:3], 0, v[0:1]
	s_or_b64 s[14:15], vcc, s[14:15]
	v_add_u32_e32 v7, s22, v7
	global_store_dwordx4 v[2:3], v[10:13], off sc0 sc1
	s_andn2_b64 exec, exec, s[14:15]
	s_cbranch_execz .LBB0_138

.LBB0_153:
	s_lshl_b64 s[6:7], s[22:23], 2
	s_add_u32 s6, s12, s6
	s_addc_u32 s7, s13, s7
	global_store_dword v65, v80, s[6:7] sc0 sc1
.LBB0_154:
	s_or_b64 exec, exec, s[28:29]
	s_lshl_b64 s[6:7], s[22:23], 11
	s_waitcnt lgkmcnt(0)
	v_lshl_add_u64 v[78:79], v[68:69], 0, s[6:7]
	v_cvt_pk_bf16_f32 v60, v60, v61
	v_cvt_pk_bf16_f32 v61, v62, v63
	v_cvt_pk_bf16_f32 v56, v56, v57
	v_cvt_pk_bf16_f32 v57, v58, v59
	v_cvt_pk_bf16_f32 v52, v52, v53
	v_cvt_pk_bf16_f32 v53, v54, v55
	v_cvt_pk_bf16_f32 v48, v48, v49
	v_cvt_pk_bf16_f32 v49, v50, v51
	global_store_dwordx2 v[78:79], v[60:61], off sc0 sc1
	global_store_dwordx2 v[78:79], v[56:57], off offset:512 sc0 sc1
	global_store_dwordx2 v[78:79], v[52:53], off offset:1024 sc0 sc1
	global_store_dwordx2 v[78:79], v[48:49], off offset:1536 sc0 sc1
	s_and_saveexec_b64 s[6:7], s[4:5]
	s_cbranch_execz .LBB0_164
	v_lshl_add_u64 v[48:49], s[22:23], 2, v[66:67]
	global_store_dword v[48:49], v65, off sc0 sc1
	s_or_b64 exec, exec, s[6:7]
	s_cmpk_gt_i32 s2, 0x40ff
	s_cbranch_scc0 .LBB0_165

.LBB0_160:
	s_lshl_b64 s[6:7], s[16:17], 2
	s_add_u32 s6, s12, s6
	s_addc_u32 s7, s13, s7
	global_store_dword v65, v34, s[6:7] sc0 sc1
.LBB0_161:
	s_or_b64 exec, exec, s[22:23]
	s_lshl_b64 s[6:7], s[16:17], 11
	s_waitcnt lgkmcnt(0)
	v_lshl_add_u64 v[32:33], v[68:69], 0, s[6:7]
	v_cvt_pk_bf16_f32 v28, v28, v29
	v_cvt_pk_bf16_f32 v29, v30, v31
	v_cvt_pk_bf16_f32 v24, v24, v25
	v_cvt_pk_bf16_f32 v25, v26, v27
	v_cvt_pk_bf16_f32 v20, v20, v21
	v_cvt_pk_bf16_f32 v21, v22, v23
	v_cvt_pk_bf16_f32 v0, v0, v1
	v_cvt_pk_bf16_f32 v1, v2, v3
	global_store_dwordx2 v[32:33], v[28:29], off sc0 sc1
	global_store_dwordx2 v[32:33], v[24:25], off offset:512 sc0 sc1
	global_store_dwordx2 v[32:33], v[20:21], off offset:1024 sc0 sc1
	global_store_dwordx2 v[32:33], v[0:1], off offset:1536 sc0 sc1
	s_and_saveexec_b64 s[6:7], s[4:5]
	s_cbranch_execz .LBB0_163
	v_lshl_add_u64 v[0:1], s[16:17], 2, v[66:67]
	global_store_dword v[0:1], v65, off sc0 sc1

.LBB0_168:
	s_lshl_b64 s[6:7], s[2:3], 2
	s_add_u32 s6, s12, s6
	s_addc_u32 s7, s13, s7
	global_store_dword v65, v50, s[6:7] sc0 sc1
.LBB0_169:
	s_or_b64 exec, exec, s[22:23]
	s_lshl_b64 s[6:7], s[2:3], 11
	s_waitcnt lgkmcnt(0)
	v_lshl_add_u64 v[48:49], v[68:69], 0, s[6:7]
	v_cvt_pk_bf16_f32 v44, v44, v45
	v_cvt_pk_bf16_f32 v45, v46, v47
	v_cvt_pk_bf16_f32 v40, v40, v41
	v_cvt_pk_bf16_f32 v41, v42, v43
	v_cvt_pk_bf16_f32 v36, v36, v37
	v_cvt_pk_bf16_f32 v37, v38, v39
	v_cvt_pk_bf16_f32 v32, v32, v33
	v_cvt_pk_bf16_f32 v33, v34, v35
	global_store_dwordx2 v[48:49], v[44:45], off sc0 sc1
	global_store_dwordx2 v[48:49], v[40:41], off offset:512 sc0 sc1
	global_store_dwordx2 v[48:49], v[36:37], off offset:1024 sc0 sc1
	global_store_dwordx2 v[48:49], v[32:33], off offset:1536 sc0 sc1
	s_and_saveexec_b64 s[6:7], s[4:5]
	s_cbranch_execz .LBB0_171
	v_lshl_add_u64 v[32:33], s[2:3], 2, v[66:67]
	global_store_dword v[32:33], v65, off sc0 sc1

.LBB0_176:
	s_lshl_b64 s[6:7], s[14:15], 2
	s_add_u32 s6, s12, s6
	s_addc_u32 s7, s13, s7
	global_store_dword v65, v2, s[6:7] sc0 sc1
.LBB0_177:
	s_or_b64 exec, exec, s[16:17]
	s_lshl_b64 s[6:7], s[14:15], 11
	s_waitcnt lgkmcnt(0)
	v_lshl_add_u64 v[0:1], v[68:69], 0, s[6:7]
	v_cvt_pk_bf16_f32 v2, v16, v17
	v_cvt_pk_bf16_f32 v3, v18, v19
	global_store_dwordx2 v[0:1], v[2:3], off sc0 sc1
	v_cvt_pk_bf16_f32 v2, v12, v13
	v_cvt_pk_bf16_f32 v3, v14, v15
	global_store_dwordx2 v[0:1], v[2:3], off offset:512 sc0 sc1
	v_cvt_pk_bf16_f32 v2, v8, v9
	v_cvt_pk_bf16_f32 v3, v10, v11
	global_store_dwordx2 v[0:1], v[2:3], off offset:1024 sc0 sc1
	v_cvt_pk_bf16_f32 v2, v4, v5
	v_cvt_pk_bf16_f32 v3, v6, v7
	global_store_dwordx2 v[0:1], v[2:3], off offset:1536 sc0 sc1
	s_and_saveexec_b64 s[6:7], s[4:5]
	s_cbranch_execz .LBB0_140
	v_lshl_add_u64 v[0:1], s[14:15], 2, v[66:67]
	global_store_dword v[0:1], v65, off sc0 sc1
	s_branch .LBB0_140

.LBB0_261:
	ds_read_b32 v156, v151
	v_add_u32_e32 v157, s20, v149
	v_readlane_b32 s20, v233, 14
	v_lshl_or_b32 v158, s51, 8, v152
	v_readlane_b32 s21, v233, 15
	s_waitcnt lgkmcnt(0)
	v_pk_mul_f32 v[124:125], v[124:125], v[156:157] op_sel_hi:[1,0]
	v_pk_mul_f32 v[120:121], v[120:121], v[156:157] op_sel_hi:[1,0]
	v_mov_b64_e32 v[146:147], s[20:21]
	v_ashrrev_i32_e32 v159, 31, v158
	v_mad_i64_i32 v[160:161], s[20:21], v157, s47, v[146:147]
	v_pk_mul_f32 v[126:127], v[126:127], v[156:157] op_sel_hi:[1,0]
	v_pk_mul_f32 v[162:163], v[122:123], v[156:157] op_sel_hi:[1,0]
	v_cvt_pk_bf16_f32 v122, v124, v125
	v_cvt_pk_bf16_f32 v123, v126, v127
	v_cvt_pk_bf16_f32 v124, v120, v121
	v_lshlrev_b64 v[120:121], 1, v[158:159]
	v_lshl_add_u64 v[126:127], v[160:161], 0, v[120:121]
	v_cvt_pk_bf16_f32 v125, v162, v163
	global_store_dwordx4 v[126:127], v[122:125], off sc0 sc1
	v_pk_mul_f32 v[116:117], v[116:117], v[156:157] op_sel_hi:[1,0]
	v_pk_mul_f32 v[118:119], v[118:119], v[156:157] op_sel_hi:[1,0]
	v_pk_mul_f32 v[122:123], v[114:115], v[156:157] op_sel_hi:[1,0]
	v_pk_mul_f32 v[114:115], v[112:113], v[156:157] op_sel_hi:[1,0]
	v_cvt_pk_bf16_f32 v112, v116, v117
	v_cvt_pk_bf16_f32 v113, v118, v119
	s_and_b64 vcc, exec, s[0:1]
	v_cvt_pk_bf16_f32 v114, v114, v115
	v_cvt_pk_bf16_f32 v115, v122, v123
	ds_read_b32 v116, v151 offset:64
	global_store_dwordx4 v[126:127], v[112:115], off offset:256 sc0 sc1
	s_mov_b64 s[0:1], -1
	s_waitcnt lgkmcnt(0)
	v_pk_mul_f32 v[108:109], v[108:109], v[116:117] op_sel_hi:[1,0]
	v_or_b32_e32 v112, 16, v157
	v_mad_i64_i32 v[112:113], s[20:21], v112, s47, v[146:147]
	v_pk_mul_f32 v[110:111], v[110:111], v[116:117] op_sel_hi:[1,0]
	v_pk_mul_f32 v[114:115], v[106:107], v[116:117] op_sel_hi:[1,0]
	v_pk_mul_f32 v[106:107], v[104:105], v[116:117] op_sel_hi:[1,0]
	v_cvt_pk_bf16_f32 v104, v108, v109
	v_cvt_pk_bf16_f32 v105, v110, v111
	v_lshl_add_u64 v[108:109], v[112:113], 0, v[120:121]
	v_cvt_pk_bf16_f32 v106, v106, v107
	v_cvt_pk_bf16_f32 v107, v114, v115
	global_store_dwordx4 v[108:109], v[104:107], off sc0 sc1
	v_pk_mul_f32 v[100:101], v[100:101], v[116:117] op_sel_hi:[1,0]
	v_pk_mul_f32 v[102:103], v[102:103], v[116:117] op_sel_hi:[1,0]
	v_pk_mul_f32 v[104:105], v[98:99], v[116:117] op_sel_hi:[1,0]
	v_pk_mul_f32 v[98:99], v[96:97], v[116:117] op_sel_hi:[1,0]
	v_cvt_pk_bf16_f32 v96, v100, v101
	v_cvt_pk_bf16_f32 v97, v102, v103
	s_nop 0
	v_cvt_pk_bf16_f32 v98, v98, v99
	v_cvt_pk_bf16_f32 v99, v104, v105
	ds_read_b32 v100, v151 offset:128
	global_store_dwordx4 v[108:109], v[96:99], off offset:256 sc0 sc1
	s_waitcnt lgkmcnt(0)
	v_pk_mul_f32 v[92:93], v[92:93], v[100:101] op_sel_hi:[1,0]
	v_or_b32_e32 v96, 32, v157
	v_mad_i64_i32 v[96:97], s[20:21], v96, s47, v[146:147]
	v_pk_mul_f32 v[94:95], v[94:95], v[100:101] op_sel_hi:[1,0]
	v_pk_mul_f32 v[98:99], v[90:91], v[100:101] op_sel_hi:[1,0]
	v_pk_mul_f32 v[90:91], v[88:89], v[100:101] op_sel_hi:[1,0]
	v_cvt_pk_bf16_f32 v88, v92, v93
	v_cvt_pk_bf16_f32 v89, v94, v95
	v_lshl_add_u64 v[92:93], v[96:97], 0, v[120:121]
	v_cvt_pk_bf16_f32 v90, v90, v91
	v_cvt_pk_bf16_f32 v91, v98, v99
	global_store_dwordx4 v[92:93], v[88:91], off sc0 sc1
	v_pk_mul_f32 v[84:85], v[84:85], v[100:101] op_sel_hi:[1,0]
	v_pk_mul_f32 v[86:87], v[86:87], v[100:101] op_sel_hi:[1,0]
	v_pk_mul_f32 v[88:89], v[82:83], v[100:101] op_sel_hi:[1,0]
	v_pk_mul_f32 v[82:83], v[80:81], v[100:101] op_sel_hi:[1,0]
	v_cvt_pk_bf16_f32 v80, v84, v85
	v_cvt_pk_bf16_f32 v81, v86, v87
	s_nop 0
	v_cvt_pk_bf16_f32 v82, v82, v83
	v_cvt_pk_bf16_f32 v83, v88, v89
	ds_read_b32 v84, v151 offset:192
	global_store_dwordx4 v[92:93], v[80:83], off offset:256 sc0 sc1
	s_waitcnt lgkmcnt(0)
	v_pk_mul_f32 v[76:77], v[76:77], v[84:85] op_sel_hi:[1,0]
	v_or_b32_e32 v80, 48, v157
	v_mad_i64_i32 v[80:81], s[20:21], v80, s47, v[146:147]
	v_pk_mul_f32 v[78:79], v[78:79], v[84:85] op_sel_hi:[1,0]
	v_pk_mul_f32 v[82:83], v[74:75], v[84:85] op_sel_hi:[1,0]
	v_pk_mul_f32 v[74:75], v[72:73], v[84:85] op_sel_hi:[1,0]
	v_cvt_pk_bf16_f32 v72, v76, v77
	v_cvt_pk_bf16_f32 v73, v78, v79
	v_lshl_add_u64 v[76:77], v[80:81], 0, v[120:121]
	v_cvt_pk_bf16_f32 v74, v74, v75
	v_cvt_pk_bf16_f32 v75, v82, v83
	global_store_dwordx4 v[76:77], v[72:75], off sc0 sc1
	v_pk_mul_f32 v[68:69], v[68:69], v[84:85] op_sel_hi:[1,0]
	v_pk_mul_f32 v[70:71], v[70:71], v[84:85] op_sel_hi:[1,0]
	v_pk_mul_f32 v[72:73], v[66:67], v[84:85] op_sel_hi:[1,0]
	v_pk_mul_f32 v[66:67], v[64:65], v[84:85] op_sel_hi:[1,0]
	v_cvt_pk_bf16_f32 v64, v68, v69
	v_cvt_pk_bf16_f32 v65, v70, v71
	s_nop 0
	v_cvt_pk_bf16_f32 v66, v66, v67
	v_cvt_pk_bf16_f32 v67, v72, v73
	ds_read_b32 v68, v151 offset:256
	global_store_dwordx4 v[76:77], v[64:67], off offset:256 sc0 sc1
	s_waitcnt lgkmcnt(0)
	v_pk_mul_f32 v[60:61], v[60:61], v[68:69] op_sel_hi:[1,0]
	v_add_u32_e32 v64, 0x80, v157
	v_mad_i64_i32 v[64:65], s[20:21], v64, s47, v[146:147]
	v_pk_mul_f32 v[62:63], v[62:63], v[68:69] op_sel_hi:[1,0]
	v_pk_mul_f32 v[66:67], v[58:59], v[68:69] op_sel_hi:[1,0]
	v_pk_mul_f32 v[58:59], v[56:57], v[68:69] op_sel_hi:[1,0]
	v_cvt_pk_bf16_f32 v56, v60, v61
	v_cvt_pk_bf16_f32 v57, v62, v63
	v_lshl_add_u64 v[60:61], v[64:65], 0, v[120:121]
	v_cvt_pk_bf16_f32 v58, v58, v59
	v_cvt_pk_bf16_f32 v59, v66, v67
	global_store_dwordx4 v[60:61], v[56:59], off sc0 sc1
	v_pk_mul_f32 v[52:53], v[52:53], v[68:69] op_sel_hi:[1,0]
	v_pk_mul_f32 v[54:55], v[54:55], v[68:69] op_sel_hi:[1,0]
	v_pk_mul_f32 v[56:57], v[50:51], v[68:69] op_sel_hi:[1,0]
	v_pk_mul_f32 v[50:51], v[48:49], v[68:69] op_sel_hi:[1,0]
	v_cvt_pk_bf16_f32 v48, v52, v53
	v_cvt_pk_bf16_f32 v49, v54, v55
	s_nop 0
	v_cvt_pk_bf16_f32 v50, v50, v51
	v_cvt_pk_bf16_f32 v51, v56, v57
	ds_read_b32 v52, v151 offset:320
	global_store_dwordx4 v[60:61], v[48:51], off offset:256 sc0 sc1
	s_waitcnt lgkmcnt(0)
	v_pk_mul_f32 v[44:45], v[44:45], v[52:53] op_sel_hi:[1,0]
	v_add_u32_e32 v48, 0x90, v157
	v_mad_i64_i32 v[48:49], s[20:21], v48, s47, v[146:147]
	v_pk_mul_f32 v[46:47], v[46:47], v[52:53] op_sel_hi:[1,0]
	v_pk_mul_f32 v[50:51], v[42:43], v[52:53] op_sel_hi:[1,0]
	v_pk_mul_f32 v[42:43], v[40:41], v[52:53] op_sel_hi:[1,0]
	v_cvt_pk_bf16_f32 v40, v44, v45
	v_cvt_pk_bf16_f32 v41, v46, v47
	v_lshl_add_u64 v[44:45], v[48:49], 0, v[120:121]
	v_cvt_pk_bf16_f32 v42, v42, v43
	v_cvt_pk_bf16_f32 v43, v50, v51
	global_store_dwordx4 v[44:45], v[40:43], off sc0 sc1
	v_pk_mul_f32 v[36:37], v[36:37], v[52:53] op_sel_hi:[1,0]
	v_pk_mul_f32 v[38:39], v[38:39], v[52:53] op_sel_hi:[1,0]
	v_pk_mul_f32 v[40:41], v[34:35], v[52:53] op_sel_hi:[1,0]
	v_pk_mul_f32 v[34:35], v[32:33], v[52:53] op_sel_hi:[1,0]
	v_cvt_pk_bf16_f32 v32, v36, v37
	v_cvt_pk_bf16_f32 v33, v38, v39
	s_nop 0
	v_cvt_pk_bf16_f32 v34, v34, v35
	v_cvt_pk_bf16_f32 v35, v40, v41
	ds_read_b32 v36, v151 offset:384
	global_store_dwordx4 v[44:45], v[32:35], off offset:256 sc0 sc1
	s_waitcnt lgkmcnt(0)
	v_pk_mul_f32 v[28:29], v[28:29], v[36:37] op_sel_hi:[1,0]
	v_add_u32_e32 v32, 0xa0, v157
	v_mad_i64_i32 v[32:33], s[20:21], v32, s47, v[146:147]
	v_pk_mul_f32 v[30:31], v[30:31], v[36:37] op_sel_hi:[1,0]
	v_pk_mul_f32 v[34:35], v[26:27], v[36:37] op_sel_hi:[1,0]
	v_pk_mul_f32 v[26:27], v[24:25], v[36:37] op_sel_hi:[1,0]
	v_cvt_pk_bf16_f32 v24, v28, v29
	v_cvt_pk_bf16_f32 v25, v30, v31
	v_lshl_add_u64 v[28:29], v[32:33], 0, v[120:121]
	v_cvt_pk_bf16_f32 v26, v26, v27
	v_cvt_pk_bf16_f32 v27, v34, v35
	global_store_dwordx4 v[28:29], v[24:27], off sc0 sc1
	v_pk_mul_f32 v[20:21], v[20:21], v[36:37] op_sel_hi:[1,0]
	v_pk_mul_f32 v[22:23], v[22:23], v[36:37] op_sel_hi:[1,0]
	v_pk_mul_f32 v[24:25], v[18:19], v[36:37] op_sel_hi:[1,0]
	v_pk_mul_f32 v[18:19], v[16:17], v[36:37] op_sel_hi:[1,0]
	v_cvt_pk_bf16_f32 v16, v20, v21
	v_cvt_pk_bf16_f32 v17, v22, v23
	s_nop 0
	v_cvt_pk_bf16_f32 v18, v18, v19
	v_cvt_pk_bf16_f32 v19, v24, v25
	ds_read_b32 v20, v151 offset:448
	global_store_dwordx4 v[28:29], v[16:19], off offset:256 sc0 sc1
	s_waitcnt lgkmcnt(0)
	v_pk_mul_f32 v[12:13], v[12:13], v[20:21] op_sel_hi:[1,0]
	v_add_u32_e32 v16, 0xb0, v157
	v_mad_i64_i32 v[16:17], s[20:21], v16, s47, v[146:147]
	v_pk_mul_f32 v[14:15], v[14:15], v[20:21] op_sel_hi:[1,0]
	v_pk_mul_f32 v[18:19], v[10:11], v[20:21] op_sel_hi:[1,0]
	v_pk_mul_f32 v[10:11], v[8:9], v[20:21] op_sel_hi:[1,0]
	v_cvt_pk_bf16_f32 v8, v12, v13
	v_cvt_pk_bf16_f32 v9, v14, v15
	v_lshl_add_u64 v[12:13], v[16:17], 0, v[120:121]
	v_cvt_pk_bf16_f32 v10, v10, v11
	v_cvt_pk_bf16_f32 v11, v18, v19
	global_store_dwordx4 v[12:13], v[8:11], off sc0 sc1
	v_pk_mul_f32 v[6:7], v[6:7], v[20:21] op_sel_hi:[1,0]
	v_pk_mul_f32 v[4:5], v[4:5], v[20:21] op_sel_hi:[1,0]
	v_pk_mul_f32 v[8:9], v[2:3], v[20:21] op_sel_hi:[1,0]
	v_pk_mul_f32 v[2:3], v[0:1], v[20:21] op_sel_hi:[1,0]
	v_cvt_pk_bf16_f32 v0, v4, v5
	v_cvt_pk_bf16_f32 v1, v6, v7
	s_nop 0
	v_cvt_pk_bf16_f32 v2, v2, v3
	v_cvt_pk_bf16_f32 v3, v8, v9
	global_store_dwordx4 v[12:13], v[0:3], off offset:256 sc0 sc1
	s_cbranch_vccnz .LBB0_245
	s_andn2_b64 vcc, exec, s[8:9]
	s_cbranch_vccnz .LBB0_244
	s_barrier
	s_branch .LBB0_244

.LBB0_662:
	s_waitcnt lgkmcnt(0)
	s_barrier
	s_ashr_i32 s45, s44, 31
	v_ashrrev_i32_e32 v0, 3, v28
	v_add_u32_e32 v0, s33, v0
	v_lshlrev_b32_e32 v1, 4, v28
	v_and_b32_e32 v2, 0x70, v1
	s_lshl_b64 s[0:1], s[44:45], 13
	s_add_u32 s4, s10, s0
	v_lshlrev_b32_e32 v0, 7, v0
	ds_read_b128 v[4:7], v130 offset:36864
	s_addc_u32 s5, s11, s1
	v_ashrrev_i32_e32 v1, 31, v0
	v_lshl_add_u64 v[8:9], s[4:5], 0, v[0:1]
	v_lshl_add_u64 v[12:13], v[8:9], 0, v[2:3]
	ds_read_b128 v[8:11], v139
	v_readlane_b32 s4, v233, 34
	v_readlane_b32 s5, v233, 35
	s_add_u32 s4, s4, s0
	s_addc_u32 s5, s5, s1
	s_waitcnt lgkmcnt(1)
	global_store_dwordx4 v[12:13], v[4:7], off sc0 sc1
	s_waitcnt vmcnt(7)
	v_perm_b32 v88, v47, v88, s73
	v_lshl_add_u64 v[4:5], s[4:5], 0, v[0:1]
	v_lshl_add_u64 v[4:5], v[4:5], 0, v[2:3]
	s_add_i32 s4, 0, 0x14e00
	s_waitcnt lgkmcnt(0)
	global_store_dwordx4 v[4:5], v[8:11], off sc0 sc1
	v_readlane_b32 s4, v233, 32
	s_add_u32 s4, s4, s0
	v_readlane_b32 s5, v233, 33
	s_addc_u32 s5, s5, s1
	ds_read_b128 v[4:7], v133
	v_lshl_add_u64 v[8:9], s[4:5], 0, v[0:1]
	s_add_i32 s4, 0, 0x1ce00
	v_lshl_add_u64 v[12:13], v[8:9], 0, v[2:3]
	ds_read_b128 v[8:11], v136
	s_add_u32 s0, s84, s0
	s_addc_u32 s1, s85, s1
	v_lshl_add_u64 v[0:1], s[0:1], 0, v[0:1]
	v_lshl_add_u64 v[0:1], v[0:1], 0, v[2:3]
	s_waitcnt lgkmcnt(1)
	global_store_dwordx4 v[12:13], v[4:7], off sc0 sc1
	s_waitcnt lgkmcnt(0)
	global_store_dwordx4 v[0:1], v[8:11], off sc0 sc1
	s_barrier
	s_load_dword s0, s[82:83], 0x110
	s_addk_i32 s75, 0x80
	s_waitcnt lgkmcnt(0)
	s_add_u32 s42, s42, s0
	v_readlane_b32 s0, v233, 38
	s_addc_u32 s43, s43, s0
	s_add_i32 s78, s78, 1
	s_mov_b64 s[0:1], 0

.LBB0_680:
	v_lshlrev_b32_e32 v0, 16, v75
	v_lshlrev_b32_e32 v96, 16, v37
	v_lshlrev_b32_e32 v94, 16, v39
	v_sub_f32_e32 v0, v0, v96
	v_sub_f32_e32 v1, v96, v94
	v_lshlrev_b32_e32 v92, 16, v46
	v_lshlrev_b32_e32 v2, 16, v48
	s_waitcnt vmcnt(9)
	v_fmac_f32_e32 v96, v84, v0
	v_sub_f32_e32 v0, v94, v92
	v_fmac_f32_e32 v94, v1, v84
	v_sub_f32_e32 v1, v92, v2
	v_lshlrev_b32_e32 v4, 16, v27
	v_lshlrev_b32_e32 v5, 16, v43
	v_fmac_f32_e32 v92, v0, v84
	v_fma_f32 v90, v1, v84, v2
	v_lshlrev_b32_e32 v1, 16, v38
	v_lshlrev_b32_e32 v0, 16, v76
	v_lshlrev_b32_e32 v7, 16, v50
	v_mov_b32_e32 v6, v1
	v_pk_add_f32 v[0:1], v[0:1], v[4:5] neg_lo:[0,1] neg_hi:[0,1]
	v_lshlrev_b32_e32 v11, 16, v42
	s_waitcnt vmcnt(8)
	v_pk_fma_f32 v[8:9], v[22:23], v[0:1], v[4:5] op_sel_hi:[0,1,1]
	v_lshlrev_b32_e32 v10, 16, v25
	v_pk_add_f32 v[4:5], v[4:5], v[6:7] neg_lo:[0,1] neg_hi:[0,1]
	v_lshlrev_b32_e32 v95, 16, v55
	v_lshlrev_b32_e32 v93, 16, v62
	v_pk_add_f32 v[0:1], v[10:11], -1.0 op_sel_hi:[1,0]
	v_pk_fma_f32 v[14:15], v[4:5], v[22:23], v[6:7] op_sel_hi:[1,0,1]
	v_sub_f32_e32 v2, v2, v95
	v_sub_f32_e32 v6, v95, v93
	v_lshlrev_b32_e32 v91, 16, v64
	v_lshlrev_b32_e32 v89, 16, v72
	s_waitcnt vmcnt(6)
	v_mul_f32_e32 v97, v85, v8
	s_waitcnt vmcnt(5)
	v_pk_fma_f32 v[0:1], v[0:1], v[26:27], 1.0 op_sel_hi:[1,0,0]
	v_lshlrev_b32_e32 v18, 16, v59
	v_fmac_f32_e32 v95, v2, v84
	v_sub_f32_e32 v2, v93, v91
	v_fmac_f32_e32 v93, v6, v84
	v_lshlrev_b32_e32 v19, 16, v70
	v_sub_f32_e32 v6, v91, v89
	v_lshlrev_b32_e32 v12, 16, v40
	v_lshlrev_b32_e32 v13, 16, v49
	v_mul_f32_e32 v29, v97, v97
	v_pk_mul_f32 v[0:1], v[8:9], v[0:1]
	v_mul_f32_e32 v98, v85, v14
	v_mul_f32_e32 v99, v85, v9
	v_lshlrev_b32_e32 v8, 16, v53
	v_lshlrev_b32_e32 v9, 16, v65
	v_fmac_f32_e32 v89, v6, v84
	v_pk_mov_b32 v[6:7], v[6:7], v[18:19] op_sel:[1,0]
	v_mul_f32_e32 v34, v98, v98
	v_pk_add_f32 v[4:5], v[12:13], -1.0 op_sel_hi:[1,0]
	v_pk_add_f32 v[6:7], v[6:7], v[8:9] neg_lo:[0,1] neg_hi:[0,1]
	v_add_f32_dpp v119, v29, v29 quad_perm:[1,0,3,2] row_mask:0xf bank_mask:0xf
	v_pk_fma_f32 v[4:5], v[4:5], v[26:27], 1.0 op_sel_hi:[1,0,0]
	v_mul_f32_e32 v102, v99, v99
	v_mul_f32_e32 v100, v85, v15
	v_pk_fma_f32 v[30:31], v[6:7], v[22:23], v[8:9] op_sel_hi:[1,0,1]
	v_pk_add_f32 v[8:9], v[8:9], v[18:19] neg_lo:[0,1] neg_hi:[0,1]
	v_add_f32_dpp v29, v34, v34 quad_perm:[1,0,3,2] row_mask:0xf bank_mask:0xf
	v_pk_mul_f32 v[4:5], v[14:15], v[4:5]
	v_mul_f32_e32 v106, v100, v100
	v_mul_f32_e32 v104, v85, v30
	v_lshlrev_b32_e32 v15, 16, v67
	v_lshlrev_b32_e32 v14, 16, v58
	v_pk_fma_f32 v[18:19], v[8:9], v[22:23], v[18:19] op_sel_hi:[1,0,1]
	v_add_f32_dpp v34, v102, v102 quad_perm:[1,0,3,2] row_mask:0xf bank_mask:0xf
	v_lshlrev_b32_e32 v16, 16, v60
	v_lshlrev_b32_e32 v17, 16, v73
	v_fmac_f32_e32 v91, v2, v84
	v_mul_f32_e32 v2, v104, v104
	v_pk_add_f32 v[6:7], v[14:15], -1.0 op_sel_hi:[1,0]
	v_mul_f32_e32 v110, v85, v18
	v_add_f32_dpp v102, v106, v106 quad_perm:[1,0,3,2] row_mask:0xf bank_mask:0xf
	v_pk_fma_f32 v[6:7], v[6:7], v[26:27], 1.0 op_sel_hi:[1,0,0]
	v_mul_f32_e32 v113, v110, v110
	v_pk_add_f32 v[8:9], v[16:17], -1.0 op_sel_hi:[1,0]
	v_mul_f32_e32 v111, v85, v31
	v_add_f32_dpp v106, v2, v2 quad_perm:[1,0,3,2] row_mask:0xf bank_mask:0xf
	v_pk_mul_f32 v[6:7], v[30:31], v[6:7]
	v_pk_fma_f32 v[8:9], v[8:9], v[26:27], 1.0 op_sel_hi:[1,0,0]
	v_mul_f32_e32 v31, v111, v111
	v_mul_f32_e32 v112, v85, v19
	v_add_f32_dpp v2, v113, v113 quad_perm:[1,0,3,2] row_mask:0xf bank_mask:0xf
	v_mul_f32_e32 v32, v96, v0
	v_pk_mul_f32 v[8:9], v[18:19], v[8:9]
	v_mul_f32_e32 v19, v112, v112
	v_add_f32_dpp v113, v31, v31 quad_perm:[1,0,3,2] row_mask:0xf bank_mask:0xf
	s_waitcnt vmcnt(4)
	v_mul_f32_e32 v33, v86, v32
	v_mul_f32_e32 v35, v94, v4
	v_add_f32_dpp v31, v19, v19 quad_perm:[1,0,3,2] row_mask:0xf bank_mask:0xf
	v_mul_f32_e32 v101, v86, v35
	v_mul_f32_e32 v30, v95, v6
	v_add_f32_dpp v19, v33, v33 quad_perm:[1,0,3,2] row_mask:0xf bank_mask:0xf
	v_mul_f32_e32 v109, v86, v30
	v_mul_f32_e32 v18, v93, v8
	v_add_f32_dpp v32, v101, v101 quad_perm:[1,0,3,2] row_mask:0xf bank_mask:0xf
	v_mul_f32_e32 v114, v86, v18
	v_mul_f32_e32 v115, v91, v7
	v_add_f32_dpp v101, v109, v109 quad_perm:[1,0,3,2] row_mask:0xf bank_mask:0xf
	v_mul_f32_e32 v116, v86, v115
	v_mul_f32_e32 v103, v92, v1
	v_add_f32_dpp v30, v114, v114 quad_perm:[1,0,3,2] row_mask:0xf bank_mask:0xf
	v_mul_f32_e32 v105, v86, v103
	v_add_f32_dpp v18, v116, v116 quad_perm:[1,0,3,2] row_mask:0xf bank_mask:0xf
	s_nop 0
	v_add_f32_dpp v33, v105, v105 quad_perm:[1,0,3,2] row_mask:0xf bank_mask:0xf
	v_add_f32_dpp v105, v119, v119 quad_perm:[2,3,0,1] row_mask:0xf bank_mask:0xf bound_ctrl:1
	v_add_f32_dpp v18, v18, v18 quad_perm:[2,3,0,1] row_mask:0xf bank_mask:0xf bound_ctrl:1
	v_add_f32_dpp v29, v29, v29 quad_perm:[2,3,0,1] row_mask:0xf bank_mask:0xf bound_ctrl:1
	v_add_f32_dpp v105, v105, v105 row_shr:4 row_mask:0xf bank_mask:0xf bound_ctrl:1
	v_add_f32_dpp v18, v18, v18 row_shr:4 row_mask:0xf bank_mask:0xf bound_ctrl:1
	v_mul_f32_e32 v107, v90, v5
	v_add_f32_dpp v105, v105, v105 row_shr:8 row_mask:0xf bank_mask:0xf bound_ctrl:1
	v_add_f32_dpp v116, v18, v18 row_shr:8 row_mask:0xf bank_mask:0xf bound_ctrl:1
	v_add_f32_dpp v29, v29, v29 row_shr:4 row_mask:0xf bank_mask:0xf bound_ctrl:1
	v_mul_f32_e32 v108, v86, v107
	v_add_f32_dpp v34, v34, v34 quad_perm:[2,3,0,1] row_mask:0xf bank_mask:0xf bound_ctrl:1
	v_add_f32_dpp v29, v29, v29 row_shr:8 row_mask:0xf bank_mask:0xf bound_ctrl:1
	v_add_f32_dpp v105, v105, v105 row_bcast:15 row_mask:0xa bank_mask:0xf
	v_add_f32_dpp v34, v34, v34 row_shr:4 row_mask:0xf bank_mask:0xf bound_ctrl:1
	v_add_f32_dpp v35, v108, v108 quad_perm:[1,0,3,2] row_mask:0xf bank_mask:0xf
	v_add_f32_dpp v102, v102, v102 quad_perm:[2,3,0,1] row_mask:0xf bank_mask:0xf bound_ctrl:1
	v_add_f32_dpp v106, v106, v106 quad_perm:[2,3,0,1] row_mask:0xf bank_mask:0xf bound_ctrl:1
	v_add_f32_dpp v107, v113, v113 quad_perm:[2,3,0,1] row_mask:0xf bank_mask:0xf bound_ctrl:1
	v_add_f32_dpp v34, v34, v34 row_shr:8 row_mask:0xf bank_mask:0xf bound_ctrl:1
	v_add_f32_dpp v113, v29, v29 row_bcast:15 row_mask:0xa bank_mask:0xf
	v_add_f32_dpp v102, v102, v102 row_shr:4 row_mask:0xf bank_mask:0xf bound_ctrl:1
	v_add_f32_dpp v106, v106, v106 row_shr:4 row_mask:0xf bank_mask:0xf bound_ctrl:1
	v_add_f32_dpp v101, v101, v101 quad_perm:[2,3,0,1] row_mask:0xf bank_mask:0xf bound_ctrl:1
	v_add_f32_dpp v102, v102, v102 row_shr:8 row_mask:0xf bank_mask:0xf bound_ctrl:1
	v_add_f32_dpp v108, v106, v106 row_shr:8 row_mask:0xf bank_mask:0xf bound_ctrl:1
	v_add_f32_dpp v106, v34, v34 row_bcast:15 row_mask:0xa bank_mask:0xf
	v_add_f32_dpp v101, v101, v101 row_shr:4 row_mask:0xf bank_mask:0xf bound_ctrl:1
	s_nop 0
	v_add_f32_dpp v2, v2, v2 quad_perm:[2,3,0,1] row_mask:0xf bank_mask:0xf bound_ctrl:1
	v_add_f32_dpp v32, v32, v32 quad_perm:[2,3,0,1] row_mask:0xf bank_mask:0xf bound_ctrl:1
	v_add_f32_dpp v115, v101, v101 row_shr:8 row_mask:0xf bank_mask:0xf bound_ctrl:1
	v_add_f32_dpp v101, v102, v102 row_bcast:15 row_mask:0xa bank_mask:0xf
	v_add_f32_dpp v2, v2, v2 row_shr:4 row_mask:0xf bank_mask:0xf bound_ctrl:1
	v_add_f32_dpp v32, v32, v32 row_shr:4 row_mask:0xf bank_mask:0xf bound_ctrl:1
	s_nop 0
	v_add_f32_dpp v2, v2, v2 row_shr:8 row_mask:0xf bank_mask:0xf bound_ctrl:1
	v_add_f32_dpp v109, v32, v32 row_shr:8 row_mask:0xf bank_mask:0xf bound_ctrl:1
	v_add_f32_dpp v32, v108, v108 row_bcast:15 row_mask:0xa bank_mask:0xf
	v_add_f32_dpp v107, v107, v107 row_shr:4 row_mask:0xf bank_mask:0xf bound_ctrl:1
	s_nop 0
	v_add_f32_dpp v31, v31, v31 quad_perm:[2,3,0,1] row_mask:0xf bank_mask:0xf bound_ctrl:1
	v_add_f32_dpp v107, v107, v107 row_shr:8 row_mask:0xf bank_mask:0xf bound_ctrl:1
	v_add_f32_dpp v29, v2, v2 row_bcast:15 row_mask:0xa bank_mask:0xf
	v_add_f32_dpp v31, v31, v31 row_shr:4 row_mask:0xf bank_mask:0xf bound_ctrl:1
	v_add_f32_dpp v19, v19, v19 quad_perm:[2,3,0,1] row_mask:0xf bank_mask:0xf bound_ctrl:1
	s_nop 0
	v_add_f32_dpp v31, v31, v31 row_shr:8 row_mask:0xf bank_mask:0xf bound_ctrl:1
	v_add_f32_dpp v18, v107, v107 row_bcast:15 row_mask:0xa bank_mask:0xf
	v_add_f32_dpp v19, v19, v19 row_shr:4 row_mask:0xf bank_mask:0xf bound_ctrl:1
	v_mul_f32_e32 v117, v89, v9
	s_nop 0
	v_add_f32_dpp v19, v19, v19 row_shr:8 row_mask:0xf bank_mask:0xf bound_ctrl:1
	v_add_f32_dpp v2, v31, v31 row_bcast:15 row_mask:0xa bank_mask:0xf
	v_mul_f32_e32 v118, v86, v117
	s_nop 0
	v_add_f32_dpp v33, v33, v33 quad_perm:[2,3,0,1] row_mask:0xf bank_mask:0xf bound_ctrl:1
	v_add_f32_dpp v34, v19, v19 row_bcast:15 row_mask:0xa bank_mask:0xf
	s_nop 0
	v_add_f32_dpp v33, v33, v33 row_shr:4 row_mask:0xf bank_mask:0xf bound_ctrl:1
	v_add_f32_dpp v103, v118, v118 quad_perm:[1,0,3,2] row_mask:0xf bank_mask:0xf
	v_add_f32_dpp v35, v35, v35 quad_perm:[2,3,0,1] row_mask:0xf bank_mask:0xf bound_ctrl:1
	v_add_f32_dpp v33, v33, v33 row_shr:8 row_mask:0xf bank_mask:0xf bound_ctrl:1
	v_add_f32_dpp v117, v109, v109 row_bcast:15 row_mask:0xa bank_mask:0xf
	v_add_f32_dpp v35, v35, v35 row_shr:4 row_mask:0xf bank_mask:0xf bound_ctrl:1
	v_add_f32_dpp v30, v30, v30 quad_perm:[2,3,0,1] row_mask:0xf bank_mask:0xf bound_ctrl:1
	s_nop 0
	v_add_f32_dpp v35, v35, v35 row_shr:8 row_mask:0xf bank_mask:0xf bound_ctrl:1
	v_add_f32_dpp v114, v33, v33 row_bcast:15 row_mask:0xa bank_mask:0xf
	v_add_f32_dpp v30, v30, v30 row_shr:4 row_mask:0xf bank_mask:0xf bound_ctrl:1
	s_ashr_i32 s0, s44, 11
	v_add_f32_dpp v107, v35, v35 row_bcast:15 row_mask:0xa bank_mask:0xf
	v_add_f32_dpp v30, v30, v30 row_shr:8 row_mask:0xf bank_mask:0xf bound_ctrl:1
	s_lshl_b32 s4, s44, 6
	v_add_f32_dpp v102, v115, v115 row_bcast:15 row_mask:0xa bank_mask:0xf
	v_add_f32_dpp v103, v103, v103 quad_perm:[2,3,0,1] row_mask:0xf bank_mask:0xf bound_ctrl:1
	s_ashr_i32 s1, s0, 31
	v_add_f32_dpp v33, v30, v30 row_bcast:15 row_mask:0xa bank_mask:0xf
	s_and_b32 s4, s4, 0x1fc0
	v_add_f32_dpp v103, v103, v103 row_shr:4 row_mask:0xf bank_mask:0xf bound_ctrl:1
	s_lshl_b64 s[0:1], s[0:1], 13
	s_nop 0
	v_add_f32_dpp v103, v103, v103 row_shr:8 row_mask:0xf bank_mask:0xf bound_ctrl:1
	v_add_f32_dpp v30, v116, v116 row_bcast:15 row_mask:0xa bank_mask:0xf
	s_add_i32 s4, s4, s33
	s_add_u32 s0, s0, s4
	v_add_f32_dpp v19, v103, v103 row_bcast:15 row_mask:0xa bank_mask:0xf
	s_addc_u32 s1, s1, 0
	s_lshr_b32 s4, s44, 5
	s_and_b32 s4, s4, 60
	v_readlane_b32 s6, v233, 36
	v_mov_b32_e32 v28, v23
	v_add_f32_dpp v123, v105, v105 row_bcast:31 row_mask:0xc bank_mask:0xf
	v_mov_b32_e32 v121, 0
	v_mov_b32_e32 v119, 0
	v_mov_b32_e32 v116, 0
	v_mov_b32_e32 v109, 0
	v_mov_b32_e32 v105, 0
	v_mov_b32_e32 v35, 0
	v_mov_b32_e32 v31, 0
	v_add_f32_dpp v126, v34, v34 row_bcast:31 row_mask:0xc bank_mask:0xf
	v_mov_b32_e32 v122, 0
	v_mov_b32_e32 v120, 0
	v_mov_b32_e32 v118, 0
	v_mov_b32_e32 v115, 0
	v_mov_b32_e32 v108, 0
	v_mov_b32_e32 v103, 0
	v_mov_b32_e32 v34, 0
	v_readlane_b32 s7, v233, 37
	s_add_u32 s22, s6, s4
	v_mov_b32_dpp v121, v113 row_bcast:31 row_mask:0xc bank_mask:0xf
	v_mov_b32_dpp v119, v106 row_bcast:31 row_mask:0xc bank_mask:0xf
	v_mov_b32_dpp v116, v101 row_bcast:31 row_mask:0xc bank_mask:0xf
	v_mov_b32_dpp v109, v32 row_bcast:31 row_mask:0xc bank_mask:0xf
	v_mov_b32_dpp v105, v29 row_bcast:31 row_mask:0xc bank_mask:0xf
	v_mov_b32_dpp v35, v18 row_bcast:31 row_mask:0xc bank_mask:0xf
	v_mov_b32_dpp v31, v2 row_bcast:31 row_mask:0xc bank_mask:0xf
	v_mov_b32_dpp v122, v117 row_bcast:31 row_mask:0xc bank_mask:0xf
	v_mov_b32_dpp v120, v114 row_bcast:31 row_mask:0xc bank_mask:0xf
	v_mov_b32_dpp v118, v107 row_bcast:31 row_mask:0xc bank_mask:0xf
	v_mov_b32_dpp v115, v102 row_bcast:31 row_mask:0xc bank_mask:0xf
	v_mov_b32_dpp v108, v33 row_bcast:31 row_mask:0xc bank_mask:0xf
	v_mov_b32_dpp v103, v30 row_bcast:31 row_mask:0xc bank_mask:0xf
	v_mov_b32_dpp v34, v19 row_bcast:31 row_mask:0xc bank_mask:0xf
	v_cmp_eq_u32_e32 vcc, 0, v28
	s_addc_u32 s23, s7, 0
	v_readlane_b32 s6, v123, 63
	v_readlane_b32 s7, v126, 63
	s_and_saveexec_b64 s[4:5], vcc
	s_cbranch_execz .LBB0_682
	s_lshl_b64 s[8:9], s[0:1], 6
	s_add_u32 s8, s22, s8
	s_addc_u32 s9, s23, s9
	v_mov_b32_e32 v123, s7
	global_store_dword v3, v123, s[8:9] sc0 sc1
.LBB0_682:
	s_or_b64 exec, exec, s[4:5]
	v_add_f32_e32 v113, v113, v121
	v_add_f32_e32 v117, v117, v122
	v_readlane_b32 s7, v113, 63
	v_readlane_b32 s8, v117, 63
	s_and_saveexec_b64 s[4:5], vcc
	s_cbranch_execz .LBB0_684
	s_lshl_b64 s[18:19], s[0:1], 6
	s_add_u32 s18, s22, s18
	s_addc_u32 s19, s23, s19
	v_mov_b32_e32 v113, s8
	global_store_dword v3, v113, s[18:19] offset:64 sc0 sc1
.LBB0_684:
	s_or_b64 exec, exec, s[4:5]
	v_add_f32_e32 v106, v106, v119
	v_add_f32_e32 v113, v114, v120
	v_readlane_b32 s8, v106, 63
	v_readlane_b32 s9, v113, 63
	s_and_saveexec_b64 s[4:5], vcc
	s_cbranch_execz .LBB0_686
	s_lshl_b64 s[18:19], s[0:1], 6
	s_add_u32 s18, s22, s18
	s_addc_u32 s19, s23, s19
	v_mov_b32_e32 v106, s9
	global_store_dword v3, v106, s[18:19] offset:128 sc0 sc1
.LBB0_686:
	s_or_b64 exec, exec, s[4:5]
	v_add_f32_e32 v101, v101, v116
	v_add_f32_e32 v106, v107, v118
	v_readlane_b32 s9, v101, 63
	v_readlane_b32 s17, v106, 63
	s_and_saveexec_b64 s[4:5], vcc
	s_cbranch_execz .LBB0_688
	s_lshl_b64 s[18:19], s[0:1], 6
	s_add_u32 s18, s22, s18
	s_addc_u32 s19, s23, s19
	v_mov_b32_e32 v101, s17
	global_store_dword v3, v101, s[18:19] offset:192 sc0 sc1
.LBB0_688:
	s_or_b64 exec, exec, s[4:5]
	v_add_f32_e32 v32, v32, v109
	v_add_f32_e32 v101, v102, v115
	v_readlane_b32 s17, v32, 63
	v_readlane_b32 s18, v101, 63
	s_and_saveexec_b64 s[4:5], vcc
	s_cbranch_execz .LBB0_690
	s_lshl_b64 s[46:47], s[0:1], 6
	s_add_u32 s46, s22, s46
	s_addc_u32 s47, s23, s47
	v_mov_b32_e32 v32, s18
	global_store_dword v3, v32, s[46:47] offset:256 sc0 sc1
.LBB0_690:
	s_or_b64 exec, exec, s[4:5]
	v_add_f32_e32 v29, v29, v105
	v_add_f32_e32 v32, v33, v108
	v_readlane_b32 s18, v29, 63
	v_readlane_b32 s19, v32, 63
	s_and_saveexec_b64 s[4:5], vcc
	s_cbranch_execz .LBB0_692
	s_lshl_b64 s[46:47], s[0:1], 6
	s_add_u32 s46, s22, s46
	s_addc_u32 s47, s23, s47
	v_mov_b32_e32 v29, s19
	global_store_dword v3, v29, s[46:47] offset:320 sc0 sc1
.LBB0_692:
	s_or_b64 exec, exec, s[4:5]
	v_add_f32_e32 v18, v18, v35
	v_add_f32_e32 v29, v30, v103
	v_readlane_b32 s19, v18, 63
	v_readlane_b32 s45, v29, 63
	s_and_saveexec_b64 s[4:5], vcc
	s_cbranch_execz .LBB0_694
	s_lshl_b64 s[46:47], s[0:1], 6
	s_add_u32 s46, s22, s46
	s_addc_u32 s47, s23, s47
	v_mov_b32_e32 v18, s45
	global_store_dword v3, v18, s[46:47] offset:384 sc0 sc1
.LBB0_694:
	s_or_b64 exec, exec, s[4:5]
	v_add_f32_e32 v2, v2, v31
	v_add_f32_e32 v18, v19, v34
	v_readlane_b32 s46, v2, 63
	v_readlane_b32 s45, v18, 63
	s_and_saveexec_b64 s[4:5], vcc
	s_cbranch_execz .LBB0_696
	s_lshl_b64 s[0:1], s[0:1], 6
	s_add_u32 s0, s22, s0
	s_addc_u32 s1, s23, s1
	v_mov_b32_e32 v2, s45
	global_store_dword v3, v2, s[0:1] offset:448 sc0 sc1
.LBB0_696:
	s_or_b64 exec, exec, s[4:5]
	v_lshlrev_b32_e32 v2, 16, v36
	v_add_f32_e32 v109, 0, v2
	v_lshlrev_b32_e32 v2, 16, v41
	v_add_f32_e32 v108, v109, v2
	v_lshlrev_b32_e32 v2, 16, v44
	v_add_f32_e32 v107, v108, v2
	v_lshlrev_b32_e32 v2, 16, v51
	v_add_f32_e32 v106, v107, v2
	v_lshlrev_b32_e32 v2, 16, v57
	v_add_f32_e32 v105, v106, v2
	v_lshlrev_b32_e32 v2, 16, v63
	v_add_f32_e32 v103, v105, v2
	v_lshlrev_b32_e32 v2, 16, v68
	v_add_f32_e32 v102, v103, v2
	v_lshlrev_b32_e32 v2, 16, v74
	v_add_f32_e32 v101, v102, v2
	ds_write_b32 v158, v101
	s_waitcnt lgkmcnt(0)
	s_barrier
	ds_read2st64_b32 v[34:35], v148 offset1:1
	ds_read2st64_b32 v[32:33], v148 offset0:2 offset1:3
	ds_read2st64_b32 v[30:31], v148 offset0:4 offset1:5
	ds_read2st64_b32 v[18:19], v148 offset0:6 offset1:7
	v_cndmask_b32_e64 v29, 0, 1, s[24:25]
	s_waitcnt lgkmcnt(3)
	v_add_f32_e32 v34, 0, v34
	v_add_f32_e32 v2, v34, v35
	s_waitcnt lgkmcnt(2)
	v_add_f32_e32 v2, v2, v32
	v_add_f32_e32 v2, v2, v33
	s_waitcnt lgkmcnt(1)
	v_add_f32_e32 v2, v2, v30
	v_add_f32_e32 v2, v2, v31
	s_waitcnt lgkmcnt(0)
	v_add_f32_e32 v2, v2, v18
	v_add_f32_e32 v2, v2, v19
	v_mul_f32_e32 v2, 0x3fb8aa3b, v2
	v_exp_f32_e32 v2, v2
	v_cmp_ne_u32_e64 s[22:23], 1, v29
	s_andn2_b64 vcc, exec, s[24:25]
	s_cbranch_vccnz .LBB0_698
	s_ashr_i32 s45, s44, 31
	s_lshl_b64 s[0:1], s[44:45], 8
	s_add_u32 s0, s50, s0
	s_addc_u32 s1, s51, s1
	v_ashrrev_i32_e32 v29, 31, v28
	v_lshl_add_u64 v[114:115], v[28:29], 2, s[0:1]
	global_store_dword v[114:115], v2, off sc0 sc1
